# conv item rewritten: LDS-DMA staged rows (2 passes), replaces serialized load ladder
# speedup vs baseline: 1.0117x; 1.0030x over previous
; __device__ __forceinline__ unsigned pk2(float lo, float hi) { f32x2 v = {lo, hi}; bf16x2_t b = __builtin_convertvector(v, bf16x2_t); return __builtin_bit_cast(unsigned, b); }
; __device__ __forceinline__ void conv_loadu(const bf16* P, int row, int seq0, int seqlen, int ch, float (&u)[8]) {
;     const int t = row - seq0;
;     if (t < 0 || t >= seqlen) {
; #pragma unroll
;         for (int i = 0; i < 8; ++i) u[i] = 0.f;
;     } else {
;         const u32x4 a = *(const u32x4*)(P + (size_t)row * PS + C_AIN + ch), c = *(const u32x4*)(P + (size_t)row * PS + C_AC + ch);
;         u[0] = bflo(a.x) * bflo(c.x); u[1] = bfhi(a.x) * bfhi(c.x); u[2] = bflo(a.y) * bflo(c.y); u[3] = bfhi(a.y) * bfhi(c.y);
;         u[4] = bflo(a.z) * bflo(c.z); u[5] = bfhi(a.z) * bfhi(c.z); u[6] = bflo(a.w) * bflo(c.w); u[7] = bfhi(a.w) * bfhi(c.w);
;     }
; }
; __device__ __forceinline__ void conv_item(const bf16* P, const float* cw, bf16* A, int item, int tid) {
;     const int rbase = item * 64, ch = (tid & 63) * 8, r0 = rbase + (tid >> 6) * 8;
;     const int seqlen = rbase >= ML ? CTX : SEQ, seq0 = rbase >= ML ? ML + ((rbase - ML) / CTX) * CTX : (rbase / SEQ) * SEQ;
;     float w0[8], w1[8], w2[8];
; #pragma unroll
;     for (int i = 0; i < 8; ++i) { w0[i] = cw[ch + i]; w1[i] = cw[512 + ch + i]; w2[i] = cw[1024 + ch + i]; }
;     float up[8], uc[8], un[8];
;     conv_loadu(P, r0 - 1, seq0, seqlen, ch, up); conv_loadu(P, r0, seq0, seqlen, ch, uc);
; #pragma unroll
;     for (int r = 0; r < 8; ++r) {
;         conv_loadu(P, r0 + r + 1, seq0, seqlen, ch, un);
;         const u32x4 b = *(const u32x4*)(P + (size_t)(r0 + r) * PS + C_AB + ch);
;         float o[8];
; #pragma unroll
;         for (int i = 0; i < 8; ++i) o[i] = w0[i] * up[i] + w1[i] * uc[i] + w2[i] * un[i];
;         o[0] *= bflo(b.x); o[1] *= bfhi(b.x); o[2] *= bflo(b.y); o[3] *= bfhi(b.y); o[4] *= bflo(b.z); o[5] *= bfhi(b.z); o[6] *= bflo(b.w); o[7] *= bfhi(b.w);
;         u32x4 w; w.x = pk2(o[0], o[1]); w.y = pk2(o[2], o[3]); w.z = pk2(o[4], o[5]); w.w = pk2(o[6], o[7]);
;         *(u32x4*)(A + (size_t)(r0 + r) * DM + ch) = w;
; #pragma unroll
;         for (int i = 0; i < 8; ++i) { up[i] = uc[i]; uc[i] = un[i]; }
;     }
; }
.LBB0_443:
	global_load_dwordx4 v[8:11], v[110:111], off offset:16
	global_load_dwordx4 v[12:15], v[110:111], off
	global_load_dwordx4 v[16:19], v[110:111], off offset:2064
	global_load_dwordx4 v[20:23], v[110:111], off offset:2048
	global_load_dwordx4 v[0:3], v[112:113], off offset:16
	global_load_dwordx4 v[4:7], v[112:113], off
	v_readfirstlane_b32 s22, v127
	v_add_u32_e32 v24, s8, v127
	v_and_b32_e32 v25, 63, v166
	s_lshl_b32 s9, s22, 11
	s_add_i32 s22, s22, s8
	s_and_b64 s[6:7], s[6:7], exec
	s_movk_i32 s4, 0x2000
	s_cselect_b32 s8, 0x100, s4
	v_lshl_add_u32 v25, v25, 4, s9
	v_ashrrev_i32_e32 v29, 31, v24
	v_mov_b32_e32 v28, v24
	v_lshlrev_b64 v[28:29], 12, v[28:29]
	v_lshl_add_u64 v[28:29], v[114:115], 0, v[28:29]
	v_mad_i64_i32 v[26:27], vcc, v24, s90, v[156:157]
	s_sub_i32 s4, s22, s21
	s_add_i32 s4, s4, -1
	s_cmp_lt_u32 s4, s8
	s_cselect_b32 s4, 0xffffa000, 0
	s_ashr_i32 s23, s4, 31
	v_add_co_u32_e32 v26, vcc, s4, v26
	v_mov_b32_e32 v238, s23
	s_nop 0
	v_addc_co_u32_e32 v27, vcc, v238, v27, vcc
	s_mov_b32 m0, s9
	s_nop 0
	global_load_lds_dwordx4 v[26:27], off
	v_add_co_u32_e32 v26, vcc, 0x800, v26
	s_nop 1
	v_addc_co_u32_e32 v27, vcc, 0, v27, vcc
	s_add_i32 m0, s9, 1024
	s_nop 0
	global_load_lds_dwordx4 v[26:27], off
	v_add_co_u32_e32 v26, vcc, 0xfffff800, v26
	s_nop 1
	v_addc_co_u32_e32 v27, vcc, -1, v27, vcc
	s_sub_i32 s4, 0, s4
	s_ashr_i32 s23, s4, 31
	v_add_co_u32_e32 v26, vcc, s4, v26
	v_mov_b32_e32 v238, s23
	s_nop 0
	v_addc_co_u32_e32 v27, vcc, v238, v27, vcc
	s_add_i32 m0, s9, 2048
	s_nop 0
	global_load_lds_dwordx4 v[26:27], off
	global_load_lds_dwordx4 v[26:27], off offset:1024
	global_load_lds_dwordx4 v[26:27], off offset:2048
	v_add_co_u32_e32 v26, vcc, 0x6000, v26
	s_nop 1
	v_addc_co_u32_e32 v27, vcc, 0, v27, vcc
	s_add_i32 m0, s9, 5120
	s_nop 0
	global_load_lds_dwordx4 v[26:27], off
	global_load_lds_dwordx4 v[26:27], off offset:1024
	global_load_lds_dwordx4 v[26:27], off offset:2048
	v_add_co_u32_e32 v26, vcc, 0x6000, v26
	s_nop 1
	v_addc_co_u32_e32 v27, vcc, 0, v27, vcc
	s_add_i32 m0, s9, 8192
	s_nop 0
	global_load_lds_dwordx4 v[26:27], off
	global_load_lds_dwordx4 v[26:27], off offset:1024
	global_load_lds_dwordx4 v[26:27], off offset:2048
	v_add_co_u32_e32 v26, vcc, 0x6000, v26
	s_nop 1
	v_addc_co_u32_e32 v27, vcc, 0, v27, vcc
	s_add_i32 m0, s9, 11264
	s_nop 0
	global_load_lds_dwordx4 v[26:27], off
	global_load_lds_dwordx4 v[26:27], off offset:1024
	global_load_lds_dwordx4 v[26:27], off offset:2048
	v_add_co_u32_e32 v26, vcc, 0x6000, v26
	s_nop 1
	v_addc_co_u32_e32 v27, vcc, 0, v27, vcc
	s_add_i32 m0, s9, 14336
	s_nop 0
	global_load_lds_dwordx4 v[26:27], off
	v_add_co_u32_e32 v26, vcc, 0x800, v26
	s_nop 1
	v_addc_co_u32_e32 v27, vcc, 0, v27, vcc
	s_add_i32 m0, s9, 15360
	s_nop 0
	global_load_lds_dwordx4 v[26:27], off
	v_add_co_u32_e32 v26, vcc, 0xfffff800, v26
	s_nop 1
	v_addc_co_u32_e32 v27, vcc, -1, v27, vcc
	v_add_co_u32_e32 v26, vcc, 0x6000, v26
	s_nop 1
	v_addc_co_u32_e32 v27, vcc, 0, v27, vcc
	s_waitcnt vmcnt(0)
	ds_read_b128 v[60:63], v25
	ds_read_b128 v[64:67], v25 offset:1024
	s_waitcnt lgkmcnt(0)
	v_lshlrev_b32_e32 v238, 16, v60
	v_and_b32_e32 v239, 0xffff0000, v60
	v_lshlrev_b32_e32 v240, 16, v64
	v_and_b32_e32 v241, 0xffff0000, v64
	v_pk_mul_f32 v[36:37], v[238:239], v[240:241]
	v_lshlrev_b32_e32 v238, 16, v61
	v_and_b32_e32 v239, 0xffff0000, v61
	v_lshlrev_b32_e32 v240, 16, v65
	v_and_b32_e32 v241, 0xffff0000, v65
	v_pk_mul_f32 v[38:39], v[238:239], v[240:241]
	v_lshlrev_b32_e32 v238, 16, v62
	v_and_b32_e32 v239, 0xffff0000, v62
	v_lshlrev_b32_e32 v240, 16, v66
	v_and_b32_e32 v241, 0xffff0000, v66
	v_pk_mul_f32 v[40:41], v[238:239], v[240:241]
	v_lshlrev_b32_e32 v238, 16, v63
	v_and_b32_e32 v239, 0xffff0000, v63
	v_lshlrev_b32_e32 v240, 16, v67
	v_and_b32_e32 v241, 0xffff0000, v67
	v_pk_mul_f32 v[42:43], v[238:239], v[240:241]
	s_sub_i32 s4, s22, s21
	s_add_i32 s4, s4, -1
	s_cmp_lt_u32 s4, s8
	s_cbranch_scc1 .Lcv_lo_ok
	v_mov_b32_e32 v36, 0
	v_mov_b32_e32 v37, 0
	v_mov_b32_e32 v38, 0
	v_mov_b32_e32 v39, 0
	v_mov_b32_e32 v40, 0
	v_mov_b32_e32 v41, 0
	v_mov_b32_e32 v42, 0
	v_mov_b32_e32 v43, 0
.Lcv_lo_ok:
	ds_read_b128 v[60:63], v25 offset:2048
	ds_read_b128 v[64:67], v25 offset:4096
	s_waitcnt lgkmcnt(0)
	v_lshlrev_b32_e32 v238, 16, v60
	v_and_b32_e32 v239, 0xffff0000, v60
	v_lshlrev_b32_e32 v240, 16, v64
	v_and_b32_e32 v241, 0xffff0000, v64
	v_pk_mul_f32 v[44:45], v[238:239], v[240:241]
	v_lshlrev_b32_e32 v238, 16, v61
	v_and_b32_e32 v239, 0xffff0000, v61
	v_lshlrev_b32_e32 v240, 16, v65
	v_and_b32_e32 v241, 0xffff0000, v65
	v_pk_mul_f32 v[46:47], v[238:239], v[240:241]
	v_lshlrev_b32_e32 v238, 16, v62
	v_and_b32_e32 v239, 0xffff0000, v62
	v_lshlrev_b32_e32 v240, 16, v66
	v_and_b32_e32 v241, 0xffff0000, v66
	v_pk_mul_f32 v[48:49], v[238:239], v[240:241]
	v_lshlrev_b32_e32 v238, 16, v63
	v_and_b32_e32 v239, 0xffff0000, v63
	v_lshlrev_b32_e32 v240, 16, v67
	v_and_b32_e32 v241, 0xffff0000, v67
	v_pk_mul_f32 v[50:51], v[238:239], v[240:241]
	ds_read_b128 v[60:63], v25 offset:5120
	ds_read_b128 v[64:67], v25 offset:7168
	s_waitcnt lgkmcnt(0)
	v_lshlrev_b32_e32 v238, 16, v60
	v_and_b32_e32 v239, 0xffff0000, v60
	v_lshlrev_b32_e32 v240, 16, v64
	v_and_b32_e32 v241, 0xffff0000, v64
	v_pk_mul_f32 v[52:53], v[238:239], v[240:241]
	v_lshlrev_b32_e32 v238, 16, v61
	v_and_b32_e32 v239, 0xffff0000, v61
	v_lshlrev_b32_e32 v240, 16, v65
	v_and_b32_e32 v241, 0xffff0000, v65
	v_pk_mul_f32 v[54:55], v[238:239], v[240:241]
	v_lshlrev_b32_e32 v238, 16, v62
	v_and_b32_e32 v239, 0xffff0000, v62
	v_lshlrev_b32_e32 v240, 16, v66
	v_and_b32_e32 v241, 0xffff0000, v66
	v_pk_mul_f32 v[56:57], v[238:239], v[240:241]
	v_lshlrev_b32_e32 v238, 16, v63
	v_and_b32_e32 v239, 0xffff0000, v63
	v_lshlrev_b32_e32 v240, 16, v67
	v_and_b32_e32 v241, 0xffff0000, v67
	v_pk_mul_f32 v[58:59], v[238:239], v[240:241]
	ds_read_b128 v[30:33], v25 offset:3072
	s_waitcnt lgkmcnt(0)
; __device__ __forceinline__ unsigned pk2(float lo, float hi) { f32x2 v = {lo, hi}; bf16x2_t b = __builtin_convertvector(v, bf16x2_t); return __builtin_bit_cast(unsigned, b); }
; __device__ __forceinline__ void conv_item(const bf16* P, const float* cw, bf16* A, int item, int tid) {
;     const int rbase = item * 64, ch = (tid & 63) * 8, r0 = rbase + (tid >> 6) * 8;
;     const int seqlen = rbase >= ML ? CTX : SEQ, seq0 = rbase >= ML ? ML + ((rbase - ML) / CTX) * CTX : (rbase / SEQ) * SEQ;
;     float w0[8], w1[8], w2[8];
; #pragma unroll
;     for (int i = 0; i < 8; ++i) { w0[i] = cw[ch + i]; w1[i] = cw[512 + ch + i]; w2[i] = cw[1024 + ch + i]; }
;     float up[8], uc[8], un[8];
;     conv_loadu(P, r0 - 1, seq0, seqlen, ch, up); conv_loadu(P, r0, seq0, seqlen, ch, uc);
; #pragma unroll
;     for (int r = 0; r < 8; ++r) {
;         conv_loadu(P, r0 + r + 1, seq0, seqlen, ch, un);
;         const u32x4 b = *(const u32x4*)(P + (size_t)(r0 + r) * PS + C_AB + ch);
;         float o[8];
; #pragma unroll
;         for (int i = 0; i < 8; ++i) o[i] = w0[i] * up[i] + w1[i] * uc[i] + w2[i] * un[i];
;         o[0] *= bflo(b.x); o[1] *= bfhi(b.x); o[2] *= bflo(b.y); o[3] *= bfhi(b.y); o[4] *= bflo(b.z); o[5] *= bfhi(b.z); o[6] *= bflo(b.w); o[7] *= bfhi(b.w);
;         u32x4 w; w.x = pk2(o[0], o[1]); w.y = pk2(o[2], o[3]); w.z = pk2(o[4], o[5]); w.w = pk2(o[6], o[7]);
;         *(u32x4*)(A + (size_t)(r0 + r) * DM + ch) = w;
; #pragma unroll
;         for (int i = 0; i < 8; ++i) { up[i] = uc[i]; uc[i] = un[i]; }
;     }
; }
	v_pk_mul_f32 v[246:247], v[20:21], v[44:45]
	v_lshlrev_b32_e32 v240, 16, v30
	v_and_b32_e32 v241, 0xffff0000, v30
	v_pk_fma_f32 v[246:247], v[12:13], v[36:37], v[246:247]
	v_pk_fma_f32 v[246:247], v[4:5], v[52:53], v[246:247]
	v_pk_mul_f32 v[60:61], v[246:247], v[240:241]
	v_pk_mul_f32 v[246:247], v[22:23], v[46:47]
	v_lshlrev_b32_e32 v240, 16, v31
	v_and_b32_e32 v241, 0xffff0000, v31
	v_pk_fma_f32 v[246:247], v[14:15], v[38:39], v[246:247]
	v_pk_fma_f32 v[246:247], v[6:7], v[54:55], v[246:247]
	v_pk_mul_f32 v[62:63], v[246:247], v[240:241]
	v_pk_mul_f32 v[246:247], v[16:17], v[48:49]
	v_lshlrev_b32_e32 v240, 16, v32
	v_and_b32_e32 v241, 0xffff0000, v32
	v_pk_fma_f32 v[246:247], v[8:9], v[40:41], v[246:247]
	v_pk_fma_f32 v[246:247], v[0:1], v[56:57], v[246:247]
	v_pk_mul_f32 v[64:65], v[246:247], v[240:241]
	v_pk_mul_f32 v[246:247], v[18:19], v[50:51]
	v_lshlrev_b32_e32 v240, 16, v33
	v_and_b32_e32 v241, 0xffff0000, v33
	v_pk_fma_f32 v[246:247], v[10:11], v[42:43], v[246:247]
	v_pk_fma_f32 v[246:247], v[2:3], v[58:59], v[246:247]
	v_pk_mul_f32 v[66:67], v[246:247], v[240:241]
	v_cvt_pk_bf16_f32 v60, v60, v61
	v_cvt_pk_bf16_f32 v61, v62, v63
	v_cvt_pk_bf16_f32 v62, v64, v65
	v_cvt_pk_bf16_f32 v63, v66, v67
	global_store_dwordx4 v[28:29], v[60:63], off
	v_add_co_u32_e32 v28, vcc, 0x1000, v28
	s_nop 1
	v_addc_co_u32_e32 v29, vcc, 0, v29, vcc
	ds_read_b128 v[60:63], v25 offset:8192
	ds_read_b128 v[64:67], v25 offset:10240
	s_waitcnt lgkmcnt(0)
	v_lshlrev_b32_e32 v238, 16, v60
	v_and_b32_e32 v239, 0xffff0000, v60
	v_lshlrev_b32_e32 v240, 16, v64
	v_and_b32_e32 v241, 0xffff0000, v64
	v_pk_mul_f32 v[36:37], v[238:239], v[240:241]
	v_lshlrev_b32_e32 v238, 16, v61
	v_and_b32_e32 v239, 0xffff0000, v61
	v_lshlrev_b32_e32 v240, 16, v65
	v_and_b32_e32 v241, 0xffff0000, v65
	v_pk_mul_f32 v[38:39], v[238:239], v[240:241]
	v_lshlrev_b32_e32 v238, 16, v62
	v_and_b32_e32 v239, 0xffff0000, v62
	v_lshlrev_b32_e32 v240, 16, v66
	v_and_b32_e32 v241, 0xffff0000, v66
	v_pk_mul_f32 v[40:41], v[238:239], v[240:241]
	v_lshlrev_b32_e32 v238, 16, v63
	v_and_b32_e32 v239, 0xffff0000, v63
	v_lshlrev_b32_e32 v240, 16, v67
	v_and_b32_e32 v241, 0xffff0000, v67
	v_pk_mul_f32 v[42:43], v[238:239], v[240:241]
	ds_read_b128 v[30:33], v25 offset:6144
	s_waitcnt lgkmcnt(0)
	v_pk_mul_f32 v[246:247], v[20:21], v[52:53]
	v_lshlrev_b32_e32 v240, 16, v30
	v_and_b32_e32 v241, 0xffff0000, v30
	v_pk_fma_f32 v[246:247], v[12:13], v[44:45], v[246:247]
	v_pk_fma_f32 v[246:247], v[4:5], v[36:37], v[246:247]
	v_pk_mul_f32 v[60:61], v[246:247], v[240:241]
	v_pk_mul_f32 v[246:247], v[22:23], v[54:55]
	v_lshlrev_b32_e32 v240, 16, v31
	v_and_b32_e32 v241, 0xffff0000, v31
	v_pk_fma_f32 v[246:247], v[14:15], v[46:47], v[246:247]
	v_pk_fma_f32 v[246:247], v[6:7], v[38:39], v[246:247]
	v_pk_mul_f32 v[62:63], v[246:247], v[240:241]
	v_pk_mul_f32 v[246:247], v[16:17], v[56:57]
	v_lshlrev_b32_e32 v240, 16, v32
	v_and_b32_e32 v241, 0xffff0000, v32
	v_pk_fma_f32 v[246:247], v[8:9], v[48:49], v[246:247]
	v_pk_fma_f32 v[246:247], v[0:1], v[40:41], v[246:247]
	v_pk_mul_f32 v[64:65], v[246:247], v[240:241]
	v_pk_mul_f32 v[246:247], v[18:19], v[58:59]
	v_lshlrev_b32_e32 v240, 16, v33
	v_and_b32_e32 v241, 0xffff0000, v33
	v_pk_fma_f32 v[246:247], v[10:11], v[50:51], v[246:247]
	v_pk_fma_f32 v[246:247], v[2:3], v[42:43], v[246:247]
	v_pk_mul_f32 v[66:67], v[246:247], v[240:241]
	v_cvt_pk_bf16_f32 v60, v60, v61
	v_cvt_pk_bf16_f32 v61, v62, v63
	v_cvt_pk_bf16_f32 v62, v64, v65
	v_cvt_pk_bf16_f32 v63, v66, v67
	global_store_dwordx4 v[28:29], v[60:63], off
	v_add_co_u32_e32 v28, vcc, 0x1000, v28
	s_nop 1
	v_addc_co_u32_e32 v29, vcc, 0, v29, vcc
	ds_read_b128 v[60:63], v25 offset:11264
	ds_read_b128 v[64:67], v25 offset:13312
	s_waitcnt lgkmcnt(0)
	v_lshlrev_b32_e32 v238, 16, v60
	v_and_b32_e32 v239, 0xffff0000, v60
	v_lshlrev_b32_e32 v240, 16, v64
	v_and_b32_e32 v241, 0xffff0000, v64
	v_pk_mul_f32 v[44:45], v[238:239], v[240:241]
	v_lshlrev_b32_e32 v238, 16, v61
	v_and_b32_e32 v239, 0xffff0000, v61
	v_lshlrev_b32_e32 v240, 16, v65
	v_and_b32_e32 v241, 0xffff0000, v65
	v_pk_mul_f32 v[46:47], v[238:239], v[240:241]
	v_lshlrev_b32_e32 v238, 16, v62
	v_and_b32_e32 v239, 0xffff0000, v62
	v_lshlrev_b32_e32 v240, 16, v66
	v_and_b32_e32 v241, 0xffff0000, v66
	v_pk_mul_f32 v[48:49], v[238:239], v[240:241]
	v_lshlrev_b32_e32 v238, 16, v63
	v_and_b32_e32 v239, 0xffff0000, v63
	v_lshlrev_b32_e32 v240, 16, v67
	v_and_b32_e32 v241, 0xffff0000, v67
	v_pk_mul_f32 v[50:51], v[238:239], v[240:241]
	ds_read_b128 v[30:33], v25 offset:9216
	s_waitcnt lgkmcnt(0)
	v_pk_mul_f32 v[246:247], v[20:21], v[36:37]
	v_lshlrev_b32_e32 v240, 16, v30
	v_and_b32_e32 v241, 0xffff0000, v30
	v_pk_fma_f32 v[246:247], v[12:13], v[52:53], v[246:247]
	v_pk_fma_f32 v[246:247], v[4:5], v[44:45], v[246:247]
	v_pk_mul_f32 v[60:61], v[246:247], v[240:241]
	v_pk_mul_f32 v[246:247], v[22:23], v[38:39]
	v_lshlrev_b32_e32 v240, 16, v31
	v_and_b32_e32 v241, 0xffff0000, v31
	v_pk_fma_f32 v[246:247], v[14:15], v[54:55], v[246:247]
	v_pk_fma_f32 v[246:247], v[6:7], v[46:47], v[246:247]
	v_pk_mul_f32 v[62:63], v[246:247], v[240:241]
	v_pk_mul_f32 v[246:247], v[16:17], v[40:41]
	v_lshlrev_b32_e32 v240, 16, v32
	v_and_b32_e32 v241, 0xffff0000, v32
	v_pk_fma_f32 v[246:247], v[8:9], v[56:57], v[246:247]
	v_pk_fma_f32 v[246:247], v[0:1], v[48:49], v[246:247]
	v_pk_mul_f32 v[64:65], v[246:247], v[240:241]
	v_pk_mul_f32 v[246:247], v[18:19], v[42:43]
	v_lshlrev_b32_e32 v240, 16, v33
	v_and_b32_e32 v241, 0xffff0000, v33
	v_pk_fma_f32 v[246:247], v[10:11], v[58:59], v[246:247]
	v_pk_fma_f32 v[246:247], v[2:3], v[50:51], v[246:247]
	v_pk_mul_f32 v[66:67], v[246:247], v[240:241]
	v_cvt_pk_bf16_f32 v60, v60, v61
	v_cvt_pk_bf16_f32 v61, v62, v63
	v_cvt_pk_bf16_f32 v62, v64, v65
	v_cvt_pk_bf16_f32 v63, v66, v67
	global_store_dwordx4 v[28:29], v[60:63], off
	v_add_co_u32_e32 v28, vcc, 0x1000, v28
	s_nop 1
	v_addc_co_u32_e32 v29, vcc, 0, v29, vcc
	ds_read_b128 v[60:63], v25 offset:14336
	ds_read_b128 v[64:67], v25 offset:15360
	s_waitcnt lgkmcnt(0)
; __device__ __forceinline__ unsigned pk2(float lo, float hi) { f32x2 v = {lo, hi}; bf16x2_t b = __builtin_convertvector(v, bf16x2_t); return __builtin_bit_cast(unsigned, b); }
; __device__ __forceinline__ void conv_item(const bf16* P, const float* cw, bf16* A, int item, int tid) {
;     const int rbase = item * 64, ch = (tid & 63) * 8, r0 = rbase + (tid >> 6) * 8;
;     const int seqlen = rbase >= ML ? CTX : SEQ, seq0 = rbase >= ML ? ML + ((rbase - ML) / CTX) * CTX : (rbase / SEQ) * SEQ;
;     float w0[8], w1[8], w2[8];
; #pragma unroll
;     for (int i = 0; i < 8; ++i) { w0[i] = cw[ch + i]; w1[i] = cw[512 + ch + i]; w2[i] = cw[1024 + ch + i]; }
;     float up[8], uc[8], un[8];
;     conv_loadu(P, r0 - 1, seq0, seqlen, ch, up); conv_loadu(P, r0, seq0, seqlen, ch, uc);
; #pragma unroll
;     for (int r = 0; r < 8; ++r) {
;         conv_loadu(P, r0 + r + 1, seq0, seqlen, ch, un);
;         const u32x4 b = *(const u32x4*)(P + (size_t)(r0 + r) * PS + C_AB + ch);
;         float o[8];
; #pragma unroll
;         for (int i = 0; i < 8; ++i) o[i] = w0[i] * up[i] + w1[i] * uc[i] + w2[i] * un[i];
;         o[0] *= bflo(b.x); o[1] *= bfhi(b.x); o[2] *= bflo(b.y); o[3] *= bfhi(b.y); o[4] *= bflo(b.z); o[5] *= bfhi(b.z); o[6] *= bflo(b.w); o[7] *= bfhi(b.w);
;         u32x4 w; w.x = pk2(o[0], o[1]); w.y = pk2(o[2], o[3]); w.z = pk2(o[4], o[5]); w.w = pk2(o[6], o[7]);
;         *(u32x4*)(A + (size_t)(r0 + r) * DM + ch) = w;
; #pragma unroll
;         for (int i = 0; i < 8; ++i) { up[i] = uc[i]; uc[i] = un[i]; }
;     }
; }
	v_lshlrev_b32_e32 v238, 16, v60
	v_and_b32_e32 v239, 0xffff0000, v60
	v_lshlrev_b32_e32 v240, 16, v64
	v_and_b32_e32 v241, 0xffff0000, v64
	v_pk_mul_f32 v[52:53], v[238:239], v[240:241]
	v_lshlrev_b32_e32 v238, 16, v61
	v_and_b32_e32 v239, 0xffff0000, v61
	v_lshlrev_b32_e32 v240, 16, v65
	v_and_b32_e32 v241, 0xffff0000, v65
	v_pk_mul_f32 v[54:55], v[238:239], v[240:241]
	v_lshlrev_b32_e32 v238, 16, v62
	v_and_b32_e32 v239, 0xffff0000, v62
	v_lshlrev_b32_e32 v240, 16, v66
	v_and_b32_e32 v241, 0xffff0000, v66
	v_pk_mul_f32 v[56:57], v[238:239], v[240:241]
	v_lshlrev_b32_e32 v238, 16, v63
	v_and_b32_e32 v239, 0xffff0000, v63
	v_lshlrev_b32_e32 v240, 16, v67
	v_and_b32_e32 v241, 0xffff0000, v67
	v_pk_mul_f32 v[58:59], v[238:239], v[240:241]
	ds_read_b128 v[30:33], v25 offset:12288
	s_waitcnt lgkmcnt(0)
	v_pk_mul_f32 v[246:247], v[20:21], v[44:45]
	v_lshlrev_b32_e32 v240, 16, v30
	v_and_b32_e32 v241, 0xffff0000, v30
	v_pk_fma_f32 v[246:247], v[12:13], v[36:37], v[246:247]
	v_pk_fma_f32 v[246:247], v[4:5], v[52:53], v[246:247]
	v_pk_mul_f32 v[60:61], v[246:247], v[240:241]
	v_pk_mul_f32 v[246:247], v[22:23], v[46:47]
	v_lshlrev_b32_e32 v240, 16, v31
	v_and_b32_e32 v241, 0xffff0000, v31
	v_pk_fma_f32 v[246:247], v[14:15], v[38:39], v[246:247]
	v_pk_fma_f32 v[246:247], v[6:7], v[54:55], v[246:247]
	v_pk_mul_f32 v[62:63], v[246:247], v[240:241]
	v_pk_mul_f32 v[246:247], v[16:17], v[48:49]
	v_lshlrev_b32_e32 v240, 16, v32
	v_and_b32_e32 v241, 0xffff0000, v32
	v_pk_fma_f32 v[246:247], v[8:9], v[40:41], v[246:247]
	v_pk_fma_f32 v[246:247], v[0:1], v[56:57], v[246:247]
	v_pk_mul_f32 v[64:65], v[246:247], v[240:241]
	v_pk_mul_f32 v[246:247], v[18:19], v[50:51]
	v_lshlrev_b32_e32 v240, 16, v33
	v_and_b32_e32 v241, 0xffff0000, v33
	v_pk_fma_f32 v[246:247], v[10:11], v[42:43], v[246:247]
	v_pk_fma_f32 v[246:247], v[2:3], v[58:59], v[246:247]
	v_pk_mul_f32 v[66:67], v[246:247], v[240:241]
	v_cvt_pk_bf16_f32 v60, v60, v61
	v_cvt_pk_bf16_f32 v61, v62, v63
	v_cvt_pk_bf16_f32 v62, v64, v65
	v_cvt_pk_bf16_f32 v63, v66, v67
	global_store_dwordx4 v[28:29], v[60:63], off
	v_add_co_u32_e32 v28, vcc, 0x1000, v28
	s_nop 1
	v_addc_co_u32_e32 v29, vcc, 0, v29, vcc
	v_add_co_u32_e32 v26, vcc, 0xffffa000, v26
	s_nop 1
	v_addc_co_u32_e32 v27, vcc, -1, v27, vcc
	s_add_i32 m0, s9, 2048
	s_nop 0
	global_load_lds_dwordx4 v[26:27], off offset:1024
	v_add_co_u32_e32 v26, vcc, 0x6000, v26
	s_nop 1
	v_addc_co_u32_e32 v27, vcc, 0, v27, vcc
	s_add_i32 m0, s9, 5120
	s_nop 0
	global_load_lds_dwordx4 v[26:27], off
	global_load_lds_dwordx4 v[26:27], off offset:1024
	global_load_lds_dwordx4 v[26:27], off offset:2048
	v_add_co_u32_e32 v26, vcc, 0x6000, v26
	s_nop 1
	v_addc_co_u32_e32 v27, vcc, 0, v27, vcc
	s_add_i32 m0, s9, 8192
	s_nop 0
	global_load_lds_dwordx4 v[26:27], off
	global_load_lds_dwordx4 v[26:27], off offset:1024
	global_load_lds_dwordx4 v[26:27], off offset:2048
	v_add_co_u32_e32 v26, vcc, 0x6000, v26
	s_nop 1
	v_addc_co_u32_e32 v27, vcc, 0, v27, vcc
	s_add_i32 m0, s9, 11264
	s_nop 0
	global_load_lds_dwordx4 v[26:27], off
	global_load_lds_dwordx4 v[26:27], off offset:1024
	global_load_lds_dwordx4 v[26:27], off offset:2048
	s_sub_i32 s4, s22, s21
	s_add_i32 s4, s4, 8
	s_cmp_lt_u32 s4, s8
	s_cselect_b32 s4, 0x6000, 0
	s_ashr_i32 s23, s4, 31
	v_add_co_u32_e32 v26, vcc, s4, v26
	v_mov_b32_e32 v238, s23
	s_nop 0
	v_addc_co_u32_e32 v27, vcc, v238, v27, vcc
	s_add_i32 m0, s9, 14336
	s_nop 0
	global_load_lds_dwordx4 v[26:27], off
	v_add_co_u32_e32 v26, vcc, 0x800, v26
	s_nop 1
	v_addc_co_u32_e32 v27, vcc, 0, v27, vcc
	s_add_i32 m0, s9, 15360
	s_nop 0
	global_load_lds_dwordx4 v[26:27], off
	s_waitcnt vmcnt(0)
	ds_read_b128 v[60:63], v25 offset:5120
	ds_read_b128 v[64:67], v25 offset:7168
	s_waitcnt lgkmcnt(0)
	v_lshlrev_b32_e32 v238, 16, v60
	v_and_b32_e32 v239, 0xffff0000, v60
	v_lshlrev_b32_e32 v240, 16, v64
	v_and_b32_e32 v241, 0xffff0000, v64
	v_pk_mul_f32 v[36:37], v[238:239], v[240:241]
	v_lshlrev_b32_e32 v238, 16, v61
	v_and_b32_e32 v239, 0xffff0000, v61
	v_lshlrev_b32_e32 v240, 16, v65
	v_and_b32_e32 v241, 0xffff0000, v65
	v_pk_mul_f32 v[38:39], v[238:239], v[240:241]
	v_lshlrev_b32_e32 v238, 16, v62
	v_and_b32_e32 v239, 0xffff0000, v62
	v_lshlrev_b32_e32 v240, 16, v66
	v_and_b32_e32 v241, 0xffff0000, v66
	v_pk_mul_f32 v[40:41], v[238:239], v[240:241]
	v_lshlrev_b32_e32 v238, 16, v63
	v_and_b32_e32 v239, 0xffff0000, v63
	v_lshlrev_b32_e32 v240, 16, v67
	v_and_b32_e32 v241, 0xffff0000, v67
	v_pk_mul_f32 v[42:43], v[238:239], v[240:241]
	ds_read_b128 v[30:33], v25 offset:3072
	s_waitcnt lgkmcnt(0)
	v_pk_mul_f32 v[246:247], v[20:21], v[52:53]
	v_lshlrev_b32_e32 v240, 16, v30
	v_and_b32_e32 v241, 0xffff0000, v30
	v_pk_fma_f32 v[246:247], v[12:13], v[44:45], v[246:247]
	v_pk_fma_f32 v[246:247], v[4:5], v[36:37], v[246:247]
	v_pk_mul_f32 v[60:61], v[246:247], v[240:241]
	v_pk_mul_f32 v[246:247], v[22:23], v[54:55]
	v_lshlrev_b32_e32 v240, 16, v31
	v_and_b32_e32 v241, 0xffff0000, v31
	v_pk_fma_f32 v[246:247], v[14:15], v[46:47], v[246:247]
	v_pk_fma_f32 v[246:247], v[6:7], v[38:39], v[246:247]
	v_pk_mul_f32 v[62:63], v[246:247], v[240:241]
	v_pk_mul_f32 v[246:247], v[16:17], v[56:57]
	v_lshlrev_b32_e32 v240, 16, v32
	v_and_b32_e32 v241, 0xffff0000, v32
	v_pk_fma_f32 v[246:247], v[8:9], v[48:49], v[246:247]
	v_pk_fma_f32 v[246:247], v[0:1], v[40:41], v[246:247]
	v_pk_mul_f32 v[64:65], v[246:247], v[240:241]
	v_pk_mul_f32 v[246:247], v[18:19], v[58:59]
	v_lshlrev_b32_e32 v240, 16, v33
	v_and_b32_e32 v241, 0xffff0000, v33
	v_pk_fma_f32 v[246:247], v[10:11], v[50:51], v[246:247]
	v_pk_fma_f32 v[246:247], v[2:3], v[42:43], v[246:247]
	v_pk_mul_f32 v[66:67], v[246:247], v[240:241]
	v_cvt_pk_bf16_f32 v60, v60, v61
	v_cvt_pk_bf16_f32 v61, v62, v63
	v_cvt_pk_bf16_f32 v62, v64, v65
	v_cvt_pk_bf16_f32 v63, v66, v67
	global_store_dwordx4 v[28:29], v[60:63], off
	v_add_co_u32_e32 v28, vcc, 0x1000, v28
	s_nop 1
	v_addc_co_u32_e32 v29, vcc, 0, v29, vcc
	ds_read_b128 v[60:63], v25 offset:8192
	ds_read_b128 v[64:67], v25 offset:10240
	s_waitcnt lgkmcnt(0)
; __device__ __forceinline__ unsigned pk2(float lo, float hi) { f32x2 v = {lo, hi}; bf16x2_t b = __builtin_convertvector(v, bf16x2_t); return __builtin_bit_cast(unsigned, b); }
; __device__ __forceinline__ void conv_loadu(const bf16* P, int row, int seq0, int seqlen, int ch, float (&u)[8]) {
;     const int t = row - seq0;
;     if (t < 0 || t >= seqlen) {
; #pragma unroll
;         for (int i = 0; i < 8; ++i) u[i] = 0.f;
;     } else {
;         const u32x4 a = *(const u32x4*)(P + (size_t)row * PS + C_AIN + ch), c = *(const u32x4*)(P + (size_t)row * PS + C_AC + ch);
;         u[0] = bflo(a.x) * bflo(c.x); u[1] = bfhi(a.x) * bfhi(c.x); u[2] = bflo(a.y) * bflo(c.y); u[3] = bfhi(a.y) * bfhi(c.y);
;         u[4] = bflo(a.z) * bflo(c.z); u[5] = bfhi(a.z) * bfhi(c.z); u[6] = bflo(a.w) * bflo(c.w); u[7] = bfhi(a.w) * bfhi(c.w);
;     }
; }
; __device__ __forceinline__ void conv_item(const bf16* P, const float* cw, bf16* A, int item, int tid) {
;     const int rbase = item * 64, ch = (tid & 63) * 8, r0 = rbase + (tid >> 6) * 8;
;     const int seqlen = rbase >= ML ? CTX : SEQ, seq0 = rbase >= ML ? ML + ((rbase - ML) / CTX) * CTX : (rbase / SEQ) * SEQ;
;     float w0[8], w1[8], w2[8];
; #pragma unroll
;     for (int i = 0; i < 8; ++i) { w0[i] = cw[ch + i]; w1[i] = cw[512 + ch + i]; w2[i] = cw[1024 + ch + i]; }
;     float up[8], uc[8], un[8];
;     conv_loadu(P, r0 - 1, seq0, seqlen, ch, up); conv_loadu(P, r0, seq0, seqlen, ch, uc);
; #pragma unroll
;     for (int r = 0; r < 8; ++r) {
;         conv_loadu(P, r0 + r + 1, seq0, seqlen, ch, un);
;         const u32x4 b = *(const u32x4*)(P + (size_t)(r0 + r) * PS + C_AB + ch);
;         float o[8];
; #pragma unroll
;         for (int i = 0; i < 8; ++i) o[i] = w0[i] * up[i] + w1[i] * uc[i] + w2[i] * un[i];
;         o[0] *= bflo(b.x); o[1] *= bfhi(b.x); o[2] *= bflo(b.y); o[3] *= bfhi(b.y); o[4] *= bflo(b.z); o[5] *= bfhi(b.z); o[6] *= bflo(b.w); o[7] *= bfhi(b.w);
;         u32x4 w; w.x = pk2(o[0], o[1]); w.y = pk2(o[2], o[3]); w.z = pk2(o[4], o[5]); w.w = pk2(o[6], o[7]);
;         *(u32x4*)(A + (size_t)(r0 + r) * DM + ch) = w;
; #pragma unroll
;         for (int i = 0; i < 8; ++i) { up[i] = uc[i]; uc[i] = un[i]; }
;     }
; }
	v_lshlrev_b32_e32 v238, 16, v60
	v_and_b32_e32 v239, 0xffff0000, v60
	v_lshlrev_b32_e32 v240, 16, v64
	v_and_b32_e32 v241, 0xffff0000, v64
	v_pk_mul_f32 v[44:45], v[238:239], v[240:241]
	v_lshlrev_b32_e32 v238, 16, v61
	v_and_b32_e32 v239, 0xffff0000, v61
	v_lshlrev_b32_e32 v240, 16, v65
	v_and_b32_e32 v241, 0xffff0000, v65
	v_pk_mul_f32 v[46:47], v[238:239], v[240:241]
	v_lshlrev_b32_e32 v238, 16, v62
	v_and_b32_e32 v239, 0xffff0000, v62
	v_lshlrev_b32_e32 v240, 16, v66
	v_and_b32_e32 v241, 0xffff0000, v66
	v_pk_mul_f32 v[48:49], v[238:239], v[240:241]
	v_lshlrev_b32_e32 v238, 16, v63
	v_and_b32_e32 v239, 0xffff0000, v63
	v_lshlrev_b32_e32 v240, 16, v67
	v_and_b32_e32 v241, 0xffff0000, v67
	v_pk_mul_f32 v[50:51], v[238:239], v[240:241]
	ds_read_b128 v[30:33], v25 offset:6144
	s_waitcnt lgkmcnt(0)
	v_pk_mul_f32 v[246:247], v[20:21], v[36:37]
	v_lshlrev_b32_e32 v240, 16, v30
	v_and_b32_e32 v241, 0xffff0000, v30
	v_pk_fma_f32 v[246:247], v[12:13], v[52:53], v[246:247]
	v_pk_fma_f32 v[246:247], v[4:5], v[44:45], v[246:247]
	v_pk_mul_f32 v[60:61], v[246:247], v[240:241]
	v_pk_mul_f32 v[246:247], v[22:23], v[38:39]
	v_lshlrev_b32_e32 v240, 16, v31
	v_and_b32_e32 v241, 0xffff0000, v31
	v_pk_fma_f32 v[246:247], v[14:15], v[54:55], v[246:247]
	v_pk_fma_f32 v[246:247], v[6:7], v[46:47], v[246:247]
	v_pk_mul_f32 v[62:63], v[246:247], v[240:241]
	v_pk_mul_f32 v[246:247], v[16:17], v[40:41]
	v_lshlrev_b32_e32 v240, 16, v32
	v_and_b32_e32 v241, 0xffff0000, v32
	v_pk_fma_f32 v[246:247], v[8:9], v[56:57], v[246:247]
	v_pk_fma_f32 v[246:247], v[0:1], v[48:49], v[246:247]
	v_pk_mul_f32 v[64:65], v[246:247], v[240:241]
	v_pk_mul_f32 v[246:247], v[18:19], v[42:43]
	v_lshlrev_b32_e32 v240, 16, v33
	v_and_b32_e32 v241, 0xffff0000, v33
	v_pk_fma_f32 v[246:247], v[10:11], v[58:59], v[246:247]
	v_pk_fma_f32 v[246:247], v[2:3], v[50:51], v[246:247]
	v_pk_mul_f32 v[66:67], v[246:247], v[240:241]
	v_cvt_pk_bf16_f32 v60, v60, v61
	v_cvt_pk_bf16_f32 v61, v62, v63
	v_cvt_pk_bf16_f32 v62, v64, v65
	v_cvt_pk_bf16_f32 v63, v66, v67
	global_store_dwordx4 v[28:29], v[60:63], off
	v_add_co_u32_e32 v28, vcc, 0x1000, v28
	s_nop 1
	v_addc_co_u32_e32 v29, vcc, 0, v29, vcc
	ds_read_b128 v[60:63], v25 offset:11264
	ds_read_b128 v[64:67], v25 offset:13312
	s_waitcnt lgkmcnt(0)
	v_lshlrev_b32_e32 v238, 16, v60
	v_and_b32_e32 v239, 0xffff0000, v60
	v_lshlrev_b32_e32 v240, 16, v64
	v_and_b32_e32 v241, 0xffff0000, v64
	v_pk_mul_f32 v[52:53], v[238:239], v[240:241]
	v_lshlrev_b32_e32 v238, 16, v61
	v_and_b32_e32 v239, 0xffff0000, v61
	v_lshlrev_b32_e32 v240, 16, v65
	v_and_b32_e32 v241, 0xffff0000, v65
	v_pk_mul_f32 v[54:55], v[238:239], v[240:241]
	v_lshlrev_b32_e32 v238, 16, v62
	v_and_b32_e32 v239, 0xffff0000, v62
	v_lshlrev_b32_e32 v240, 16, v66
	v_and_b32_e32 v241, 0xffff0000, v66
	v_pk_mul_f32 v[56:57], v[238:239], v[240:241]
	v_lshlrev_b32_e32 v238, 16, v63
	v_and_b32_e32 v239, 0xffff0000, v63
	v_lshlrev_b32_e32 v240, 16, v67
	v_and_b32_e32 v241, 0xffff0000, v67
	v_pk_mul_f32 v[58:59], v[238:239], v[240:241]
	ds_read_b128 v[30:33], v25 offset:9216
	s_waitcnt lgkmcnt(0)
	v_pk_mul_f32 v[246:247], v[20:21], v[44:45]
	v_lshlrev_b32_e32 v240, 16, v30
	v_and_b32_e32 v241, 0xffff0000, v30
	v_pk_fma_f32 v[246:247], v[12:13], v[36:37], v[246:247]
	v_pk_fma_f32 v[246:247], v[4:5], v[52:53], v[246:247]
	v_pk_mul_f32 v[60:61], v[246:247], v[240:241]
	v_pk_mul_f32 v[246:247], v[22:23], v[46:47]
	v_lshlrev_b32_e32 v240, 16, v31
	v_and_b32_e32 v241, 0xffff0000, v31
	v_pk_fma_f32 v[246:247], v[14:15], v[38:39], v[246:247]
	v_pk_fma_f32 v[246:247], v[6:7], v[54:55], v[246:247]
	v_pk_mul_f32 v[62:63], v[246:247], v[240:241]
	v_pk_mul_f32 v[246:247], v[16:17], v[48:49]
	v_lshlrev_b32_e32 v240, 16, v32
	v_and_b32_e32 v241, 0xffff0000, v32
	v_pk_fma_f32 v[246:247], v[8:9], v[40:41], v[246:247]
	v_pk_fma_f32 v[246:247], v[0:1], v[56:57], v[246:247]
	v_pk_mul_f32 v[64:65], v[246:247], v[240:241]
	v_pk_mul_f32 v[246:247], v[18:19], v[50:51]
	v_lshlrev_b32_e32 v240, 16, v33
	v_and_b32_e32 v241, 0xffff0000, v33
	v_pk_fma_f32 v[246:247], v[10:11], v[42:43], v[246:247]
	v_pk_fma_f32 v[246:247], v[2:3], v[58:59], v[246:247]
	v_pk_mul_f32 v[66:67], v[246:247], v[240:241]
	v_cvt_pk_bf16_f32 v60, v60, v61
	v_cvt_pk_bf16_f32 v61, v62, v63
	v_cvt_pk_bf16_f32 v62, v64, v65
	v_cvt_pk_bf16_f32 v63, v66, v67
	global_store_dwordx4 v[28:29], v[60:63], off
	v_add_co_u32_e32 v28, vcc, 0x1000, v28
	s_nop 1
	v_addc_co_u32_e32 v29, vcc, 0, v29, vcc
	ds_read_b128 v[60:63], v25 offset:14336
	ds_read_b128 v[64:67], v25 offset:15360
	s_waitcnt lgkmcnt(0)
	v_lshlrev_b32_e32 v238, 16, v60
	v_and_b32_e32 v239, 0xffff0000, v60
	v_lshlrev_b32_e32 v240, 16, v64
	v_and_b32_e32 v241, 0xffff0000, v64
	v_pk_mul_f32 v[36:37], v[238:239], v[240:241]
	v_lshlrev_b32_e32 v238, 16, v61
	v_and_b32_e32 v239, 0xffff0000, v61
	v_lshlrev_b32_e32 v240, 16, v65
	v_and_b32_e32 v241, 0xffff0000, v65
	v_pk_mul_f32 v[38:39], v[238:239], v[240:241]
	v_lshlrev_b32_e32 v238, 16, v62
	v_and_b32_e32 v239, 0xffff0000, v62
	v_lshlrev_b32_e32 v240, 16, v66
	v_and_b32_e32 v241, 0xffff0000, v66
	v_pk_mul_f32 v[40:41], v[238:239], v[240:241]
	v_lshlrev_b32_e32 v238, 16, v63
	v_and_b32_e32 v239, 0xffff0000, v63
	v_lshlrev_b32_e32 v240, 16, v67
	v_and_b32_e32 v241, 0xffff0000, v67
	v_pk_mul_f32 v[42:43], v[238:239], v[240:241]
	s_sub_i32 s4, s22, s21
	s_add_i32 s4, s4, 8
	s_cmp_lt_u32 s4, s8
	s_cbranch_scc1 .Lcv_hi_ok
	v_mov_b32_e32 v36, 0
	v_mov_b32_e32 v37, 0
	v_mov_b32_e32 v38, 0
	v_mov_b32_e32 v39, 0
	v_mov_b32_e32 v40, 0
	v_mov_b32_e32 v41, 0
	v_mov_b32_e32 v42, 0
	v_mov_b32_e32 v43, 0
.Lcv_hi_ok:
	ds_read_b128 v[30:33], v25 offset:12288
	s_waitcnt lgkmcnt(0)
	v_pk_mul_f32 v[246:247], v[20:21], v[52:53]
	v_lshlrev_b32_e32 v240, 16, v30
	v_and_b32_e32 v241, 0xffff0000, v30
	v_pk_fma_f32 v[246:247], v[12:13], v[44:45], v[246:247]
	v_pk_fma_f32 v[246:247], v[4:5], v[36:37], v[246:247]
	v_pk_mul_f32 v[60:61], v[246:247], v[240:241]
	v_pk_mul_f32 v[246:247], v[22:23], v[54:55]
	v_lshlrev_b32_e32 v240, 16, v31
	v_and_b32_e32 v241, 0xffff0000, v31
	v_pk_fma_f32 v[246:247], v[14:15], v[46:47], v[246:247]
	v_pk_fma_f32 v[246:247], v[6:7], v[38:39], v[246:247]
	v_pk_mul_f32 v[62:63], v[246:247], v[240:241]
	v_pk_mul_f32 v[246:247], v[16:17], v[56:57]
	v_lshlrev_b32_e32 v240, 16, v32
	v_and_b32_e32 v241, 0xffff0000, v32
	v_pk_fma_f32 v[246:247], v[8:9], v[48:49], v[246:247]
	v_pk_fma_f32 v[246:247], v[0:1], v[40:41], v[246:247]
	v_pk_mul_f32 v[64:65], v[246:247], v[240:241]
	v_pk_mul_f32 v[246:247], v[18:19], v[58:59]
	v_lshlrev_b32_e32 v240, 16, v33
	v_and_b32_e32 v241, 0xffff0000, v33
	v_pk_fma_f32 v[246:247], v[10:11], v[50:51], v[246:247]
	v_pk_fma_f32 v[246:247], v[2:3], v[42:43], v[246:247]
	v_pk_mul_f32 v[66:67], v[246:247], v[240:241]
	v_cvt_pk_bf16_f32 v60, v60, v61
	v_cvt_pk_bf16_f32 v61, v62, v63
	v_cvt_pk_bf16_f32 v62, v64, v65
	v_cvt_pk_bf16_f32 v63, v66, v67
	global_store_dwordx4 v[28:29], v[60:63], off
	v_add_co_u32_e32 v28, vcc, 0x1000, v28
	s_nop 1
	v_addc_co_u32_e32 v29, vcc, 0, v29, vcc
	s_mov_b64 s[6:7], 0
